# first barrier also uses the XCD barrier (cooperative-groups sync removed; census completed inside the first barrier), plus direct release and tight polling
# speedup vs baseline: 1.1714x; 1.0010x over previous
; DEVI void grid_barrier(const int TIDX, const int BIDX, const int GDIM, unsigned* bar, unsigned k) {
;   __syncthreads();
;   if (TIDX == 0) {
;     __threadfence();
;     const unsigned g = (unsigned)BIDX & 7u, gs = (unsigned)GDIM >> 3;
;     const unsigned old = __hip_atomic_fetch_add(bar + 32 * (1 + g), 1u, __ATOMIC_RELAXED, __HIP_MEMORY_SCOPE_AGENT);
;     if (old + 1u == gs * k) {
;       __threadfence();
;       __hip_atomic_fetch_add(bar, 1u, __ATOMIC_RELAXED, __HIP_MEMORY_SCOPE_AGENT);
;     }
;     unsigned spins = 0;
;     while (__hip_atomic_load(bar, __ATOMIC_RELAXED, __HIP_MEMORY_SCOPE_AGENT) < 8u * k) {
;       __builtin_amdgcn_s_sleep(1);
;       if (++spins > (1u << 27)) break;
;     }
;     __threadfence();
;   }
;   __syncthreads();
; }
; __global__ void __launch_bounds__(256, 2) mega(Params p, int ph0, int ph1) {
;     ...
;     if (ph + 1 < ph1) {
;       if (ph == ph0) cg::this_grid().sync();
;       else grid_barrier(TIDX, BIDX, GDIM, (unsigned*)(WSB + O_CNT + 2048), (unsigned)(ph - ph0));
.LBB0_787:
	v_cmp_eq_u32_e32 vcc, 0, v130
	s_waitcnt vmcnt(0) lgkmcnt(0)
	s_barrier
	s_and_saveexec_b64 s[0:1], vcc
	s_cbranch_execz .LBB0_810
	s_add_u32 s2, s50, 0x22a9800
	s_addc_u32 s3, s51, 0
	s_getreg_b32 s4, hwreg(HW_REG_XCC_ID, 0, 4)
	s_lshl_b32 s4, s4, 6
	v_mov_b32_e32 v0, s4
	s_mov_b32 s10, 0x4000
	s_cmp_lg_u32 s100, 0
	s_cbranch_scc1 .Lxb_have
	v_mov_b32_e32 v1, 1
	global_atomic_add v0, v1, s[2:3]
	s_waitcnt vmcnt(0)
.Lxb_census:
	global_load_dword v3, v129, s[2:3] sc1
	global_load_dword v4, v129, s[2:3] offset:64 sc1
	global_load_dword v5, v129, s[2:3] offset:128 sc1
	global_load_dword v6, v129, s[2:3] offset:192 sc1
	global_load_dword v7, v129, s[2:3] offset:256 sc1
	global_load_dword v8, v129, s[2:3] offset:320 sc1
	global_load_dword v9, v129, s[2:3] offset:384 sc1
	global_load_dword v10, v129, s[2:3] offset:448 sc1
	global_load_dword v11, v129, s[2:3] offset:512 sc1
	global_load_dword v12, v129, s[2:3] offset:576 sc1
	global_load_dword v13, v129, s[2:3] offset:640 sc1
	global_load_dword v14, v129, s[2:3] offset:704 sc1
	global_load_dword v15, v129, s[2:3] offset:768 sc1
	global_load_dword v16, v129, s[2:3] offset:832 sc1
	global_load_dword v17, v129, s[2:3] offset:896 sc1
	global_load_dword v18, v129, s[2:3] offset:960 sc1
	s_waitcnt vmcnt(0)
	v_add_u32_e32 v3, v3, v4
	v_add_u32_e32 v3, v3, v5
	v_add_u32_e32 v3, v3, v6
	v_add_u32_e32 v3, v3, v7
	v_add_u32_e32 v3, v3, v8
	v_add_u32_e32 v3, v3, v9
	v_add_u32_e32 v3, v3, v10
	v_add_u32_e32 v3, v3, v11
	v_add_u32_e32 v3, v3, v12
	v_add_u32_e32 v3, v3, v13
	v_add_u32_e32 v3, v3, v14
	v_add_u32_e32 v3, v3, v15
	v_add_u32_e32 v3, v3, v16
	v_add_u32_e32 v3, v3, v17
	v_add_u32_e32 v3, v3, v18
	s_nop 0
	v_readfirstlane_b32 s5, v3
	s_cmp_eq_u32 s5, s84
	s_cbranch_scc1 .Lxb_census_done
	s_add_i32 s10, s10, -1
	s_cmp_eq_u32 s10, 0
	s_cbranch_scc1 .Lxb_census_done
	s_sleep 1
	s_branch .Lxb_census
.Lxb_census_done:
	global_load_dword v1, v0, s[2:3] sc1
	s_waitcnt vmcnt(0)
	v_readfirstlane_b32 s100, v1
	s_mov_b32 s10, 0x4000
.Lxb_have:
	v_readlane_b32 s6, v255, 3
	s_sub_i32 s9, s12, s6
	s_add_i32 s9, s9, 1
	v_mov_b32_e32 v1, 1
	global_atomic_add v1, v0, v1, s[2:3] offset:16 sc0
	s_mul_i32 s5, s100, s9
	s_waitcnt vmcnt(0)
	v_readfirstlane_b32 s7, v1
	s_add_i32 s7, s7, 1
	s_cmp_eq_u32 s7, s5
	s_cbranch_scc0 .Lxb_follow
	buffer_wbl2 sc1
	s_waitcnt vmcnt(0)
	v_mov_b32_e32 v1, s100
	v_mov_b32_e32 v2, 0x400
	global_atomic_add v1, v2, v1, s[2:3] sc0
	s_mul_i32 s5, s84, s9
	s_waitcnt vmcnt(0)
	v_readfirstlane_b32 s7, v1
	s_add_i32 s7, s7, s100
	s_cmp_eq_u32 s7, s5
	s_cbranch_scc0 .Lxb_follow
	v_mov_b32_e32 v1, 1
	global_atomic_add v129, v1, s[2:3] offset:32
	global_atomic_add v129, v1, s[2:3] offset:96
	global_atomic_add v129, v1, s[2:3] offset:160
	global_atomic_add v129, v1, s[2:3] offset:224
	global_atomic_add v129, v1, s[2:3] offset:288
	global_atomic_add v129, v1, s[2:3] offset:352
	global_atomic_add v129, v1, s[2:3] offset:416
	global_atomic_add v129, v1, s[2:3] offset:480
	global_atomic_add v129, v1, s[2:3] offset:544
	global_atomic_add v129, v1, s[2:3] offset:608
	global_atomic_add v129, v1, s[2:3] offset:672
	global_atomic_add v129, v1, s[2:3] offset:736
	global_atomic_add v129, v1, s[2:3] offset:800
	global_atomic_add v129, v1, s[2:3] offset:864
	global_atomic_add v129, v1, s[2:3] offset:928
	global_atomic_add v129, v1, s[2:3] offset:992
	buffer_inv sc1
	s_waitcnt vmcnt(0)
	s_branch .LBB0_810

; __global__ void __launch_bounds__(256, 2) mega(Params p, int ph0, int ph1) {
;     ...
;     if (ph + 1 < ph1) {
;       if (ph == ph0) cg::this_grid().sync();
;       else grid_barrier(TIDX, BIDX, GDIM, (unsigned*)(WSB + O_CNT + 2048), (unsigned)(ph - ph0));
.LBB0_811:
	s_getpc_b64 s[98:99]
